# attention loops: the per-tile cross-half row-max exchange uses v_permlane32_swap (two copies + swap + max) instead of a ds_bpermute round trip; bitwise identical
# speedup vs baseline: 1.0090x; 1.0090x over previous
; #define MFMA32(a, b, c) __builtin_amdgcn_mfma_f32_32x32x16_bf16((a), (b), (c), 0, 0, 0)
; #define A_LOAD(tile) do { _Pragma("unroll") for (int i = 0; i < NKC; ++i) kreg[i] = *(const u32x4*)(Kg + (size_t)(tile) * 64 * DQK + i * 32); \
;     _Pragma("unroll") for (int i = 0; i < 4; ++i) vreg[i] = *(const u32x4*)(Vg + (size_t)(tile) * 8192 + i * 2048); } while (0)
; #define A_STORE() do { _Pragma("unroll") for (int i = 0; i < NKC; ++i) *(u32x4*)(Kst + i * 64) = kreg[i]; \
;     _Pragma("unroll") for (int i = 0; i < 4; ++i) *(u32x4*)(Vst + i * 32 * 144) = vreg[i]; } while (0)
;     ...
;     __syncthreads();
;     A_STORE();
;     __syncthreads();
;     if (t + 1 < ntiles) A_LOAD(t0 + t + 1);
;     f32x16 st0, st1;
; #pragma unroll
;     for (int q = 0; q < 16; ++q) { st0[q] = 0.f; st1[q] = 0.f; }
; #pragma unroll
;     for (int ks0 = 0; ks0 < KS; ks0 += 2) {
;       bf16x8 a0[2], a1[2];
; #pragma unroll
;       for (int j = 0; j < 2; ++j) { a0[j] = *(const bf16x8*)(Krd + (ks0 + j) * 32); a1[j] = *(const bf16x8*)(Krd + 32 * KROW + (ks0 + j) * 32); }
;       __builtin_amdgcn_sched_barrier(0);
; #pragma unroll
;       for (int j = 0; j < 2; ++j) { st0 = MFMA32(a0[j], qr[ks0 + j], st0); st1 = MFMA32(a1[j], qr[ks0 + j], st1); }
;     }
;     float mx = st0[0];
; #pragma unroll
;     for (int q = 1; q < 16; ++q) mx = fmaxf(mx, st0[q]);
; #pragma unroll
;     for (int q = 0; q < 16; ++q) mx = fmaxf(mx, st1[q]);
;     mx = fmaxf(mx, __shfl_xor(mx, 32));
;     const float mnew = fmaxf(m, mx * scale_log2);
;     const float alpha = __builtin_amdgcn_exp2f(m - mnew);
;     m = mnew;
;     float ps = 0.f;
; #pragma unroll
;     for (int q = 0; q < 16; ++q) { st0[q] = __builtin_amdgcn_exp2f(st0[q] * scale_log2 - mnew); ps += st0[q]; }
; #pragma unroll
;     for (int q = 0; q < 16; ++q) { st1[q] = __builtin_amdgcn_exp2f(st1[q] * scale_log2 - mnew); ps += st1[q]; }
;     lsum = lsum * alpha + ps;
;     if (!__all(alpha == 1.f)) {
; #pragma unroll
;       for (int n = 0; n < 4; ++n)
; #pragma unroll
;         for (int q = 0; q < 16; ++q) ot[n][q] *= alpha;
.LBB0_78:
	s_waitcnt vmcnt(23)
	v_lshl_add_u64 v[64:65], v[168:169], 0, s[0:1]
	s_barrier
	s_waitcnt vmcnt(7)
	ds_write_b128 v177, v[130:133]
	s_waitcnt vmcnt(6)
	ds_write_b128 v177, v[134:137] offset:64
	s_waitcnt vmcnt(5)
	ds_write_b128 v177, v[138:141] offset:128
	s_waitcnt vmcnt(4)
	ds_write_b128 v177, v[142:145] offset:192
	s_waitcnt vmcnt(1)
	ds_write_b128 v176, v[154:157] offset:17408
	ds_write_b128 v176, v[146:149] offset:22016
	ds_write_b128 v176, v[150:153] offset:26624
	s_waitcnt vmcnt(0)
	ds_write_b128 v176, v[158:161] offset:31232
	s_waitcnt lgkmcnt(0)
	s_barrier
	global_load_dwordx4 v[130:133], v[64:65], off offset:-128
	global_load_dwordx4 v[134:137], v[64:65], off offset:-64
	global_load_dwordx4 v[138:141], v[64:65], off
	global_load_dwordx4 v[142:145], v[64:65], off offset:64
	v_lshl_add_u64 v[64:65], v[166:167], 0, s[0:1]
	v_add_co_u32_e32 v66, vcc, s64, v64
	s_nop 1
	v_addc_co_u32_e32 v67, vcc, 0, v65, vcc
	v_add_co_u32_e32 v64, vcc, s65, v64
	global_load_dwordx4 v[154:157], v[66:67], off offset:-4096
	global_load_dwordx4 v[146:149], v[66:67], off
	v_addc_co_u32_e32 v65, vcc, 0, v65, vcc
	global_load_dwordx4 v[150:153], v[64:65], off offset:-4096
	global_load_dwordx4 v[158:161], v[64:65], off
	ds_read_b128 v[64:67], v175
	ds_read_b128 v[180:183], v175 offset:32
	ds_read_b128 v[68:71], v175 offset:8704
	ds_read_b128 v[190:193], v175 offset:8736
	s_waitcnt lgkmcnt(3)
	v_mfma_f32_32x32x16_bf16 v[80:95], v[64:67], v[126:129], 0
	s_waitcnt lgkmcnt(1)
	v_mfma_f32_32x32x16_bf16 v[64:79], v[68:71], v[126:129], 0
	v_mfma_f32_32x32x16_bf16 v[80:95], v[180:183], v[122:125], v[80:95]
	s_waitcnt lgkmcnt(0)
	v_mfma_f32_32x32x16_bf16 v[64:79], v[190:193], v[122:125], v[64:79]
	ds_read_b128 v[180:183], v175 offset:8768
	ds_read_b128 v[190:193], v175 offset:64
	ds_read_b128 v[194:197], v175 offset:96
	ds_read_b128 v[198:201], v175 offset:8800
	s_waitcnt lgkmcnt(2)
	v_mfma_f32_32x32x16_bf16 v[80:95], v[190:193], v[118:121], v[80:95]
	v_mfma_f32_32x32x16_bf16 v[64:79], v[180:183], v[118:121], v[64:79]
	s_waitcnt lgkmcnt(1)
	v_mfma_f32_32x32x16_bf16 v[80:95], v[194:197], v[114:117], v[80:95]
	s_waitcnt lgkmcnt(0)
	v_mfma_f32_32x32x16_bf16 v[64:79], v[198:201], v[114:117], v[64:79]
	ds_read_b128 v[180:183], v175 offset:8832
	ds_read_b128 v[190:193], v175 offset:128
	ds_read_b128 v[194:197], v175 offset:160
	ds_read_b128 v[198:201], v175 offset:8864
	s_waitcnt lgkmcnt(2)
	v_mfma_f32_32x32x16_bf16 v[80:95], v[190:193], v[110:113], v[80:95]
	v_mfma_f32_32x32x16_bf16 v[64:79], v[180:183], v[110:113], v[64:79]
	s_waitcnt lgkmcnt(1)
	v_mfma_f32_32x32x16_bf16 v[80:95], v[194:197], v[106:109], v[80:95]
	s_waitcnt lgkmcnt(0)
	v_mfma_f32_32x32x16_bf16 v[64:79], v[198:201], v[106:109], v[64:79]
	ds_read_b128 v[180:183], v175 offset:8896
	ds_read_b128 v[190:193], v175 offset:192
	ds_read_b128 v[194:197], v175 offset:224
	ds_read_b128 v[198:201], v175 offset:8928
	s_waitcnt lgkmcnt(2)
	v_mfma_f32_32x32x16_bf16 v[80:95], v[190:193], v[102:105], v[80:95]
	s_waitcnt lgkmcnt(1)
	v_mfma_f32_32x32x16_bf16 v[80:95], v[194:197], v[98:101], v[80:95]
	v_mfma_f32_32x32x16_bf16 v[64:79], v[180:183], v[102:105], v[64:79]
	s_nop 10
	v_max_f32_e32 v170, v81, v81
	v_max_f32_e32 v178, v80, v80
	v_max_f32_e32 v170, v178, v170
	v_max3_f32 v170, v170, v82, v83
	v_max3_f32 v170, v170, v84, v85
	v_max3_f32 v170, v170, v86, v87
	v_max3_f32 v170, v170, v88, v89
	s_waitcnt lgkmcnt(0)
	v_mfma_f32_32x32x16_bf16 v[64:79], v[198:201], v[98:101], v[64:79]
	v_max3_f32 v170, v170, v90, v91
	v_max3_f32 v170, v170, v92, v93
	v_max3_f32 v170, v170, v94, v95
	v_mov_b32_e32 v180, v174
	s_nop 7
	v_max3_f32 v170, v170, v64, v65
	v_max3_f32 v170, v170, v66, v67
	v_max3_f32 v170, v170, v68, v69
	v_max3_f32 v170, v170, v70, v71
	v_max3_f32 v170, v170, v72, v73
	v_max3_f32 v170, v170, v74, v75
	v_max3_f32 v170, v170, v76, v77
	v_max3_f32 v170, v170, v78, v79
	v_mov_b32_e32 v178, v170
	v_mov_b32_e32 v174, v170
	s_nop 1
	v_permlane32_swap_b32_e32 v178, v174
	s_waitcnt lgkmcnt(0)
	v_max_f32_e32 v170, v178, v174
	v_mul_f32_e32 v170, 0x3e0293ee, v170
	v_max_f32_e32 v174, v180, v180
	v_max_f32_e32 v174, v174, v170
	v_sub_f32_e32 v170, v180, v174
	v_exp_f32_e32 v170, v170
	s_nop 0
	v_cmp_eq_f32_e32 vcc, 1.0, v170
	s_cmp_eq_u64 vcc, exec
	s_cbranch_scc1 .LBB0_80
	v_pk_mul_f32 v[46:47], v[46:47], v[170:171] op_sel_hi:[1,0]
	v_pk_mul_f32 v[44:45], v[44:45], v[170:171] op_sel_hi:[1,0]
	v_pk_mul_f32 v[42:43], v[42:43], v[170:171] op_sel_hi:[1,0]
	v_pk_mul_f32 v[40:41], v[40:41], v[170:171] op_sel_hi:[1,0]
	v_pk_mul_f32 v[38:39], v[38:39], v[170:171] op_sel_hi:[1,0]
	v_pk_mul_f32 v[36:37], v[36:37], v[170:171] op_sel_hi:[1,0]
	v_pk_mul_f32 v[34:35], v[34:35], v[170:171] op_sel_hi:[1,0]
	v_pk_mul_f32 v[32:33], v[32:33], v[170:171] op_sel_hi:[1,0]
	v_pk_mul_f32 v[62:63], v[62:63], v[170:171] op_sel_hi:[1,0]
	v_pk_mul_f32 v[60:61], v[60:61], v[170:171] op_sel_hi:[1,0]
	v_pk_mul_f32 v[58:59], v[58:59], v[170:171] op_sel_hi:[1,0]
	v_pk_mul_f32 v[56:57], v[56:57], v[170:171] op_sel_hi:[1,0]
	v_pk_mul_f32 v[54:55], v[54:55], v[170:171] op_sel_hi:[1,0]
	v_pk_mul_f32 v[52:53], v[52:53], v[170:171] op_sel_hi:[1,0]
	v_pk_mul_f32 v[50:51], v[50:51], v[170:171] op_sel_hi:[1,0]
	v_pk_mul_f32 v[48:49], v[48:49], v[170:171] op_sel_hi:[1,0]
	v_pk_mul_f32 v[30:31], v[30:31], v[170:171] op_sel_hi:[1,0]
	v_pk_mul_f32 v[28:29], v[28:29], v[170:171] op_sel_hi:[1,0]
	v_pk_mul_f32 v[26:27], v[26:27], v[170:171] op_sel_hi:[1,0]
	v_pk_mul_f32 v[24:25], v[24:25], v[170:171] op_sel_hi:[1,0]
	v_pk_mul_f32 v[22:23], v[22:23], v[170:171] op_sel_hi:[1,0]
	v_pk_mul_f32 v[20:21], v[20:21], v[170:171] op_sel_hi:[1,0]
	v_pk_mul_f32 v[18:19], v[18:19], v[170:171] op_sel_hi:[1,0]
	v_pk_mul_f32 v[16:17], v[16:17], v[170:171] op_sel_hi:[1,0]
	v_pk_mul_f32 v[14:15], v[14:15], v[170:171] op_sel_hi:[1,0]
	v_pk_mul_f32 v[12:13], v[12:13], v[170:171] op_sel_hi:[1,0]
	v_pk_mul_f32 v[10:11], v[10:11], v[170:171] op_sel_hi:[1,0]
	v_pk_mul_f32 v[8:9], v[8:9], v[170:171] op_sel_hi:[1,0]
	v_pk_mul_f32 v[6:7], v[6:7], v[170:171] op_sel_hi:[1,0]
	v_pk_mul_f32 v[4:5], v[4:5], v[170:171] op_sel_hi:[1,0]
	v_pk_mul_f32 v[2:3], v[2:3], v[170:171] op_sel_hi:[1,0]
	v_pk_mul_f32 v[0:1], v[0:1], v[170:171] op_sel_hi:[1,0]

; #define MFMA32(a, b, c) __builtin_amdgcn_mfma_f32_32x32x16_bf16((a), (b), (c), 0, 0, 0)
; #define A_LOAD(tile) do { _Pragma("unroll") for (int i = 0; i < NKC; ++i) kreg[i] = *(const u32x4*)(Kg + (size_t)(tile) * 64 * DQK + i * 32); \
;     _Pragma("unroll") for (int i = 0; i < 4; ++i) vreg[i] = *(const u32x4*)(Vg + (size_t)(tile) * 8192 + i * 2048); } while (0)
; #define A_STORE() do { _Pragma("unroll") for (int i = 0; i < NKC; ++i) *(u32x4*)(Kst + i * 64) = kreg[i]; \
;     _Pragma("unroll") for (int i = 0; i < 4; ++i) *(u32x4*)(Vst + i * 32 * 144) = vreg[i]; } while (0)
;     ...
;     __syncthreads();
;     A_STORE();
;     __syncthreads();
;     if (t + 1 < ntiles) A_LOAD(t0 + t + 1);
;     f32x16 st0, st1;
; #pragma unroll
;     for (int q = 0; q < 16; ++q) { st0[q] = 0.f; st1[q] = 0.f; }
; #pragma unroll
;     for (int ks0 = 0; ks0 < KS; ks0 += 2) {
;       bf16x8 a0[2], a1[2];
; #pragma unroll
;       for (int j = 0; j < 2; ++j) { a0[j] = *(const bf16x8*)(Krd + (ks0 + j) * 32); a1[j] = *(const bf16x8*)(Krd + 32 * KROW + (ks0 + j) * 32); }
;       __builtin_amdgcn_sched_barrier(0);
; #pragma unroll
;       for (int j = 0; j < 2; ++j) { st0 = MFMA32(a0[j], qr[ks0 + j], st0); st1 = MFMA32(a1[j], qr[ks0 + j], st1); }
;     }
;     float mx = st0[0];
; #pragma unroll
;     for (int q = 1; q < 16; ++q) mx = fmaxf(mx, st0[q]);
; #pragma unroll
;     for (int q = 0; q < 16; ++q) mx = fmaxf(mx, st1[q]);
;     mx = fmaxf(mx, __shfl_xor(mx, 32));
;     const float mnew = fmaxf(m, mx * scale_log2);
;     const float alpha = __builtin_amdgcn_exp2f(m - mnew);
;     m = mnew;
;     float ps = 0.f;
; #pragma unroll
;     for (int q = 0; q < 16; ++q) { st0[q] = __builtin_amdgcn_exp2f(st0[q] * scale_log2 - mnew); ps += st0[q]; }
; #pragma unroll
;     for (int q = 0; q < 16; ++q) { st1[q] = __builtin_amdgcn_exp2f(st1[q] * scale_log2 - mnew); ps += st1[q]; }
;     lsum = lsum * alpha + ps;
;     if (!__all(alpha == 1.f)) {
.LBB0_131:
	s_waitcnt vmcnt(29) lgkmcnt(0)
	v_lshl_add_u64 v[64:65], s[94:95], 0, v[192:193]
	s_barrier
	s_waitcnt vmcnt(9)
	ds_write_b128 v199, v[146:149]
	s_waitcnt vmcnt(8)
	ds_write_b128 v199, v[150:153] offset:64
	s_waitcnt vmcnt(7)
	ds_write_b128 v199, v[154:157] offset:128
	s_waitcnt vmcnt(6)
	ds_write_b128 v199, v[158:161] offset:192
	s_waitcnt vmcnt(5)
	ds_write_b128 v199, v[162:165] offset:256
	s_waitcnt vmcnt(4)
	ds_write_b128 v199, v[166:169] offset:320
	s_waitcnt vmcnt(1)
	ds_write_b128 v198, v[178:181] offset:25600
	ds_write_b128 v198, v[170:173] offset:30208
	ds_write_b128 v198, v[174:177] offset:34816
	s_waitcnt vmcnt(0)
	ds_write_b128 v198, v[182:185] offset:39424
	s_waitcnt lgkmcnt(0)
	s_barrier
	global_load_dwordx4 v[146:149], v[64:65], off offset:-192
	global_load_dwordx4 v[150:153], v[64:65], off offset:-128
	global_load_dwordx4 v[154:157], v[64:65], off offset:-64
	global_load_dwordx4 v[158:161], v[64:65], off
	global_load_dwordx4 v[162:165], v[64:65], off offset:64
	global_load_dwordx4 v[166:169], v[64:65], off offset:128
	v_lshl_add_u64 v[64:65], s[94:95], 0, v[190:191]
	v_add_co_u32_e32 v66, vcc, s70, v64
	s_nop 1
	v_addc_co_u32_e32 v67, vcc, 0, v65, vcc
	v_add_co_u32_e32 v64, vcc, s71, v64
	global_load_dwordx4 v[178:181], v[66:67], off offset:-4096
	global_load_dwordx4 v[170:173], v[66:67], off
	v_addc_co_u32_e32 v65, vcc, 0, v65, vcc
	global_load_dwordx4 v[174:177], v[64:65], off offset:-4096
	global_load_dwordx4 v[182:185], v[64:65], off
	ds_read_b128 v[64:67], v197
	ds_read_b128 v[218:221], v197 offset:32
	ds_read_b128 v[68:71], v197 offset:12800
	ds_read_b128 v[238:241], v197 offset:12832
	s_waitcnt lgkmcnt(3)
	v_mfma_f32_32x32x16_bf16 v[80:95], v[64:67], v[142:145], 0
	s_waitcnt lgkmcnt(1)
	v_mfma_f32_32x32x16_bf16 v[64:79], v[68:71], v[142:145], 0
	v_mfma_f32_32x32x16_bf16 v[80:95], v[218:221], v[138:141], v[80:95]
	s_waitcnt lgkmcnt(0)
	v_mfma_f32_32x32x16_bf16 v[64:79], v[238:241], v[138:141], v[64:79]
	ds_read_b128 v[218:221], v197 offset:12864
	ds_read_b128 v[238:241], v197 offset:64
	ds_read_b128 v[244:247], v197 offset:96
	ds_read_b128 v[248:251], v197 offset:12896
	s_waitcnt lgkmcnt(2)
	v_mfma_f32_32x32x16_bf16 v[80:95], v[238:241], v[134:137], v[80:95]
	v_mfma_f32_32x32x16_bf16 v[64:79], v[218:221], v[134:137], v[64:79]
	s_waitcnt lgkmcnt(1)
	v_mfma_f32_32x32x16_bf16 v[80:95], v[244:247], v[130:133], v[80:95]
	s_waitcnt lgkmcnt(0)
	v_mfma_f32_32x32x16_bf16 v[64:79], v[248:251], v[130:133], v[64:79]
	ds_read_b128 v[218:221], v197 offset:12928
	ds_read_b128 v[238:241], v197 offset:128
	ds_read_b128 v[244:247], v197 offset:160
	ds_read_b128 v[248:251], v197 offset:12960
	s_waitcnt lgkmcnt(2)
	v_mfma_f32_32x32x16_bf16 v[80:95], v[238:241], v[126:129], v[80:95]
	v_mfma_f32_32x32x16_bf16 v[64:79], v[218:221], v[126:129], v[64:79]
	s_waitcnt lgkmcnt(1)
	v_mfma_f32_32x32x16_bf16 v[80:95], v[244:247], v[122:125], v[80:95]
	s_waitcnt lgkmcnt(0)
	v_mfma_f32_32x32x16_bf16 v[64:79], v[248:251], v[122:125], v[64:79]
	ds_read_b128 v[218:221], v197 offset:12992
	ds_read_b128 v[238:241], v197 offset:192
	ds_read_b128 v[244:247], v197 offset:224
	ds_read_b128 v[248:251], v197 offset:13024
	s_waitcnt lgkmcnt(2)
	v_mfma_f32_32x32x16_bf16 v[80:95], v[238:241], v[118:121], v[80:95]
	v_mfma_f32_32x32x16_bf16 v[64:79], v[218:221], v[118:121], v[64:79]
	s_waitcnt lgkmcnt(1)
	v_mfma_f32_32x32x16_bf16 v[80:95], v[244:247], v[114:117], v[80:95]
	s_waitcnt lgkmcnt(0)
	v_mfma_f32_32x32x16_bf16 v[64:79], v[248:251], v[114:117], v[64:79]
	ds_read_b128 v[218:221], v197 offset:13056
	ds_read_b128 v[238:241], v197 offset:256
	ds_read_b128 v[244:247], v197 offset:288
	ds_read_b128 v[248:251], v197 offset:13088
	s_waitcnt lgkmcnt(2)
	v_mfma_f32_32x32x16_bf16 v[80:95], v[238:241], v[110:113], v[80:95]
	v_mfma_f32_32x32x16_bf16 v[64:79], v[218:221], v[110:113], v[64:79]
	s_waitcnt lgkmcnt(1)
	v_mfma_f32_32x32x16_bf16 v[80:95], v[244:247], v[106:109], v[80:95]
	s_waitcnt lgkmcnt(0)
	v_mfma_f32_32x32x16_bf16 v[64:79], v[248:251], v[106:109], v[64:79]
	ds_read_b128 v[218:221], v197 offset:13120
	ds_read_b128 v[238:241], v197 offset:320
	ds_read_b128 v[244:247], v197 offset:352
	ds_read_b128 v[248:251], v197 offset:13152
	s_waitcnt lgkmcnt(2)
	v_mfma_f32_32x32x16_bf16 v[80:95], v[238:241], v[102:105], v[80:95]
	v_mov_b32_e32 v202, v196
	s_waitcnt lgkmcnt(1)
	v_mfma_f32_32x32x16_bf16 v[80:95], v[244:247], v[98:101], v[80:95]
	v_mfma_f32_32x32x16_bf16 v[64:79], v[218:221], v[102:105], v[64:79]
	s_nop 10
	v_max_f32_e32 v96, v81, v81
	v_max_f32_e32 v200, v80, v80
	v_max_f32_e32 v96, v200, v96
	v_max3_f32 v96, v96, v82, v83
	v_max3_f32 v96, v96, v84, v85
	v_max3_f32 v96, v96, v86, v87
	v_max3_f32 v96, v96, v88, v89
	s_waitcnt lgkmcnt(0)
	v_mfma_f32_32x32x16_bf16 v[64:79], v[248:251], v[98:101], v[64:79]
	v_max3_f32 v96, v96, v90, v91
	v_max3_f32 v96, v96, v92, v93
	v_max3_f32 v96, v96, v94, v95
	s_nop 8
	v_max3_f32 v96, v96, v64, v65
	v_max3_f32 v96, v96, v66, v67
	v_max3_f32 v96, v96, v68, v69
	v_max3_f32 v96, v96, v70, v71
	v_max3_f32 v96, v96, v72, v73
	v_max3_f32 v96, v96, v74, v75
	v_max3_f32 v96, v96, v76, v77
	v_max3_f32 v96, v96, v78, v79
	v_mov_b32_e32 v200, v96
	v_mov_b32_e32 v196, v96
	s_nop 1
	v_permlane32_swap_b32_e32 v200, v196
	s_waitcnt lgkmcnt(0)
	v_max_f32_e32 v96, v200, v196
	v_mul_f32_e32 v96, 0x3dd53b94, v96
	v_max_f32_e32 v196, v202, v202
	v_max_f32_e32 v196, v196, v96
	v_sub_f32_e32 v96, v202, v196
	v_exp_f32_e32 v96, v96
	s_nop 0
	v_cmp_eq_f32_e32 vcc, 1.0, v96
	s_cmp_eq_u64 vcc, exec
	s_cbranch_scc1 .LBB0_133
;     ...
;     if (!__all(alpha == 1.f)) {
; #pragma unroll
;       for (int n = 0; n < 4; ++n)
; #pragma unroll
;         for (int q = 0; q < 16; ++q) ot[n][q] *= alpha;
;     }
	v_pk_mul_f32 v[62:63], v[62:63], v[96:97] op_sel_hi:[1,0]
	v_pk_mul_f32 v[60:61], v[60:61], v[96:97] op_sel_hi:[1,0]
	v_pk_mul_f32 v[58:59], v[58:59], v[96:97] op_sel_hi:[1,0]
	v_pk_mul_f32 v[56:57], v[56:57], v[96:97] op_sel_hi:[1,0]
	v_pk_mul_f32 v[54:55], v[54:55], v[96:97] op_sel_hi:[1,0]
	v_pk_mul_f32 v[52:53], v[52:53], v[96:97] op_sel_hi:[1,0]
	v_pk_mul_f32 v[50:51], v[50:51], v[96:97] op_sel_hi:[1,0]
	v_pk_mul_f32 v[48:49], v[48:49], v[96:97] op_sel_hi:[1,0]
	v_pk_mul_f32 v[46:47], v[46:47], v[96:97] op_sel_hi:[1,0]
	v_pk_mul_f32 v[44:45], v[44:45], v[96:97] op_sel_hi:[1,0]
	v_pk_mul_f32 v[42:43], v[42:43], v[96:97] op_sel_hi:[1,0]
	v_pk_mul_f32 v[40:41], v[40:41], v[96:97] op_sel_hi:[1,0]
	v_pk_mul_f32 v[38:39], v[38:39], v[96:97] op_sel_hi:[1,0]
	v_pk_mul_f32 v[36:37], v[36:37], v[96:97] op_sel_hi:[1,0]
	v_pk_mul_f32 v[34:35], v[34:35], v[96:97] op_sel_hi:[1,0]
	v_pk_mul_f32 v[32:33], v[32:33], v[96:97] op_sel_hi:[1,0]
	v_pk_mul_f32 v[30:31], v[30:31], v[96:97] op_sel_hi:[1,0]
	v_pk_mul_f32 v[28:29], v[28:29], v[96:97] op_sel_hi:[1,0]
	v_pk_mul_f32 v[26:27], v[26:27], v[96:97] op_sel_hi:[1,0]
	v_pk_mul_f32 v[24:25], v[24:25], v[96:97] op_sel_hi:[1,0]
	v_pk_mul_f32 v[22:23], v[22:23], v[96:97] op_sel_hi:[1,0]
	v_pk_mul_f32 v[20:21], v[20:21], v[96:97] op_sel_hi:[1,0]
	v_pk_mul_f32 v[18:19], v[18:19], v[96:97] op_sel_hi:[1,0]
	v_pk_mul_f32 v[16:17], v[16:17], v[96:97] op_sel_hi:[1,0]
	v_pk_mul_f32 v[14:15], v[14:15], v[96:97] op_sel_hi:[1,0]
	v_pk_mul_f32 v[12:13], v[12:13], v[96:97] op_sel_hi:[1,0]
	v_pk_mul_f32 v[10:11], v[10:11], v[96:97] op_sel_hi:[1,0]
	v_pk_mul_f32 v[8:9], v[8:9], v[96:97] op_sel_hi:[1,0]
	v_pk_mul_f32 v[6:7], v[6:7], v[96:97] op_sel_hi:[1,0]
	v_pk_mul_f32 v[4:5], v[4:5], v[96:97] op_sel_hi:[1,0]
	v_pk_mul_f32 v[2:3], v[2:3], v[96:97] op_sel_hi:[1,0]
	v_pk_mul_f32 v[0:1], v[0:1], v[96:97] op_sel_hi:[1,0]

; #define MFMA32(a, b, c) __builtin_amdgcn_mfma_f32_32x32x16_bf16((a), (b), (c), 0, 0, 0)
; #define A_LOAD(tile) do { _Pragma("unroll") for (int i = 0; i < NKC; ++i) kreg[i] = *(const u32x4*)(Kg + (size_t)(tile) * 64 * DQK + i * 32); \
;     _Pragma("unroll") for (int i = 0; i < 4; ++i) vreg[i] = *(const u32x4*)(Vg + (size_t)(tile) * 8192 + i * 2048); } while (0)
; #define A_STORE() do { _Pragma("unroll") for (int i = 0; i < NKC; ++i) *(u32x4*)(Kst + i * 64) = kreg[i]; \
;     _Pragma("unroll") for (int i = 0; i < 4; ++i) *(u32x4*)(Vst + i * 32 * 144) = vreg[i]; } while (0)
;     ...
;     __syncthreads();
;     A_STORE();
;     __syncthreads();
;     if (t + 1 < ntiles) A_LOAD(t0 + t + 1);
;     f32x16 st0, st1;
; #pragma unroll
;     for (int q = 0; q < 16; ++q) { st0[q] = 0.f; st1[q] = 0.f; }
; #pragma unroll
;     for (int ks0 = 0; ks0 < KS; ks0 += 2) {
;       bf16x8 a0[2], a1[2];
; #pragma unroll
;       for (int j = 0; j < 2; ++j) { a0[j] = *(const bf16x8*)(Krd + (ks0 + j) * 32); a1[j] = *(const bf16x8*)(Krd + 32 * KROW + (ks0 + j) * 32); }
;       __builtin_amdgcn_sched_barrier(0);
; #pragma unroll
;       for (int j = 0; j < 2; ++j) { st0 = MFMA32(a0[j], qr[ks0 + j], st0); st1 = MFMA32(a1[j], qr[ks0 + j], st1); }
;     }
;     float mx = st0[0];
; #pragma unroll
;     for (int q = 1; q < 16; ++q) mx = fmaxf(mx, st0[q]);
; #pragma unroll
;     for (int q = 0; q < 16; ++q) mx = fmaxf(mx, st1[q]);
;     mx = fmaxf(mx, __shfl_xor(mx, 32));
;     const float mnew = fmaxf(m, mx * scale_log2);
;     const float alpha = __builtin_amdgcn_exp2f(m - mnew);
;     m = mnew;
;     float ps = 0.f;
; #pragma unroll
;     for (int q = 0; q < 16; ++q) { st0[q] = __builtin_amdgcn_exp2f(st0[q] * scale_log2 - mnew); ps += st0[q]; }
; #pragma unroll
;     for (int q = 0; q < 16; ++q) { st1[q] = __builtin_amdgcn_exp2f(st1[q] * scale_log2 - mnew); ps += st1[q]; }
;     lsum = lsum * alpha + ps;
;     if (!__all(alpha == 1.f)) {
; #pragma unroll
;       for (int n = 0; n < 4; ++n)
; #pragma unroll
;         for (int q = 0; q < 16; ++q) ot[n][q] *= alpha;
.LBB0_141:
	s_waitcnt vmcnt(23) lgkmcnt(0)
	v_lshl_add_u64 v[64:65], v[166:167], 0, s[0:1]
	s_barrier
	s_waitcnt vmcnt(7)
	ds_write_b128 v173, v[130:133]
	s_waitcnt vmcnt(6)
	ds_write_b128 v173, v[134:137] offset:64
	s_waitcnt vmcnt(5)
	ds_write_b128 v173, v[138:141] offset:128
	s_waitcnt vmcnt(4)
	ds_write_b128 v173, v[142:145] offset:192
	s_waitcnt vmcnt(1)
	ds_write_b128 v172, v[154:157] offset:17408
	ds_write_b128 v172, v[146:149] offset:22016
	ds_write_b128 v172, v[150:153] offset:26624
	s_waitcnt vmcnt(0)
	ds_write_b128 v172, v[158:161] offset:31232
	s_waitcnt lgkmcnt(0)
	s_barrier
	global_load_dwordx4 v[130:133], v[64:65], off offset:-128
	global_load_dwordx4 v[134:137], v[64:65], off offset:-64
	global_load_dwordx4 v[138:141], v[64:65], off
	global_load_dwordx4 v[142:145], v[64:65], off offset:64
	v_lshl_add_u64 v[64:65], v[164:165], 0, s[0:1]
	v_add_co_u32_e32 v66, vcc, s64, v64
	s_nop 1
	v_addc_co_u32_e32 v67, vcc, 0, v65, vcc
	v_add_co_u32_e32 v64, vcc, s65, v64
	global_load_dwordx4 v[154:157], v[66:67], off offset:-4096
	global_load_dwordx4 v[146:149], v[66:67], off
	v_addc_co_u32_e32 v65, vcc, 0, v65, vcc
	global_load_dwordx4 v[150:153], v[64:65], off offset:-4096
	global_load_dwordx4 v[158:161], v[64:65], off
	ds_read_b128 v[64:67], v171
	ds_read_b128 v[176:179], v171 offset:32
	ds_read_b128 v[68:71], v171 offset:8704
	ds_read_b128 v[180:183], v171 offset:8736
	s_waitcnt lgkmcnt(3)
	v_mfma_f32_32x32x16_bf16 v[80:95], v[64:67], v[126:129], 0
	s_waitcnt lgkmcnt(1)
	v_mfma_f32_32x32x16_bf16 v[64:79], v[68:71], v[126:129], 0
	v_mfma_f32_32x32x16_bf16 v[80:95], v[176:179], v[122:125], v[80:95]
	s_waitcnt lgkmcnt(0)
	v_mfma_f32_32x32x16_bf16 v[64:79], v[180:183], v[122:125], v[64:79]
	ds_read_b128 v[176:179], v171 offset:8768
	ds_read_b128 v[180:183], v171 offset:64
	ds_read_b128 v[190:193], v171 offset:96
	ds_read_b128 v[194:197], v171 offset:8800
	s_waitcnt lgkmcnt(2)
	v_mfma_f32_32x32x16_bf16 v[80:95], v[180:183], v[118:121], v[80:95]
	v_mfma_f32_32x32x16_bf16 v[64:79], v[176:179], v[118:121], v[64:79]
	s_waitcnt lgkmcnt(1)
	v_mfma_f32_32x32x16_bf16 v[80:95], v[190:193], v[114:117], v[80:95]
	s_waitcnt lgkmcnt(0)
	v_mfma_f32_32x32x16_bf16 v[64:79], v[194:197], v[114:117], v[64:79]
	ds_read_b128 v[176:179], v171 offset:8832
	ds_read_b128 v[180:183], v171 offset:128
	ds_read_b128 v[190:193], v171 offset:160
	ds_read_b128 v[194:197], v171 offset:8864
	s_waitcnt lgkmcnt(2)
	v_mfma_f32_32x32x16_bf16 v[80:95], v[180:183], v[110:113], v[80:95]
	v_mfma_f32_32x32x16_bf16 v[64:79], v[176:179], v[110:113], v[64:79]
	s_waitcnt lgkmcnt(1)
	v_mfma_f32_32x32x16_bf16 v[80:95], v[190:193], v[106:109], v[80:95]
	s_waitcnt lgkmcnt(0)
	v_mfma_f32_32x32x16_bf16 v[64:79], v[194:197], v[106:109], v[64:79]
	ds_read_b128 v[176:179], v171 offset:8896
	ds_read_b128 v[180:183], v171 offset:192
	ds_read_b128 v[190:193], v171 offset:224
	ds_read_b128 v[194:197], v171 offset:8928
	s_waitcnt lgkmcnt(2)
	v_mfma_f32_32x32x16_bf16 v[80:95], v[180:183], v[102:105], v[80:95]
	s_waitcnt lgkmcnt(1)
	v_mfma_f32_32x32x16_bf16 v[80:95], v[190:193], v[98:101], v[80:95]
	v_mfma_f32_32x32x16_bf16 v[64:79], v[176:179], v[102:105], v[64:79]
	s_nop 10
	v_max_f32_e32 v96, v81, v81
	v_max_f32_e32 v174, v80, v80
	v_max_f32_e32 v96, v174, v96
	v_max3_f32 v96, v96, v82, v83
	v_max3_f32 v96, v96, v84, v85
	v_max3_f32 v96, v96, v86, v87
	v_max3_f32 v96, v96, v88, v89
	s_waitcnt lgkmcnt(0)
	v_mfma_f32_32x32x16_bf16 v[64:79], v[194:197], v[98:101], v[64:79]
	v_max3_f32 v96, v96, v90, v91
	v_max3_f32 v96, v96, v92, v93
	v_max3_f32 v96, v96, v94, v95
	v_mov_b32_e32 v176, v170
	s_nop 7
	v_max3_f32 v96, v96, v64, v65
	v_max3_f32 v96, v96, v66, v67
	v_max3_f32 v96, v96, v68, v69
	v_max3_f32 v96, v96, v70, v71
	v_max3_f32 v96, v96, v72, v73
	v_max3_f32 v96, v96, v74, v75
	v_max3_f32 v96, v96, v76, v77
	v_max3_f32 v96, v96, v78, v79
	v_mov_b32_e32 v174, v96
	v_mov_b32_e32 v170, v96
	s_nop 1
	v_permlane32_swap_b32_e32 v174, v170
	s_waitcnt lgkmcnt(0)
	v_max_f32_e32 v96, v174, v170
	v_mul_f32_e32 v96, 0x3e0293ee, v96
	v_max_f32_e32 v170, v176, v176
	v_max_f32_e32 v170, v170, v96
	v_sub_f32_e32 v96, v176, v170
	v_exp_f32_e32 v96, v96
	s_nop 0
	v_cmp_eq_f32_e32 vcc, 1.0, v96
	s_cmp_eq_u64 vcc, exec
	s_cbranch_scc1 .LBB0_143
	v_pk_mul_f32 v[62:63], v[62:63], v[96:97] op_sel_hi:[1,0]
	v_pk_mul_f32 v[60:61], v[60:61], v[96:97] op_sel_hi:[1,0]
	v_pk_mul_f32 v[58:59], v[58:59], v[96:97] op_sel_hi:[1,0]
	v_pk_mul_f32 v[56:57], v[56:57], v[96:97] op_sel_hi:[1,0]
	v_pk_mul_f32 v[54:55], v[54:55], v[96:97] op_sel_hi:[1,0]
	v_pk_mul_f32 v[52:53], v[52:53], v[96:97] op_sel_hi:[1,0]
	v_pk_mul_f32 v[50:51], v[50:51], v[96:97] op_sel_hi:[1,0]
	v_pk_mul_f32 v[48:49], v[48:49], v[96:97] op_sel_hi:[1,0]
	v_pk_mul_f32 v[46:47], v[46:47], v[96:97] op_sel_hi:[1,0]
	v_pk_mul_f32 v[44:45], v[44:45], v[96:97] op_sel_hi:[1,0]
	v_pk_mul_f32 v[42:43], v[42:43], v[96:97] op_sel_hi:[1,0]
	v_pk_mul_f32 v[40:41], v[40:41], v[96:97] op_sel_hi:[1,0]
	v_pk_mul_f32 v[38:39], v[38:39], v[96:97] op_sel_hi:[1,0]
	v_pk_mul_f32 v[36:37], v[36:37], v[96:97] op_sel_hi:[1,0]
	v_pk_mul_f32 v[34:35], v[34:35], v[96:97] op_sel_hi:[1,0]
	v_pk_mul_f32 v[32:33], v[32:33], v[96:97] op_sel_hi:[1,0]
	v_pk_mul_f32 v[30:31], v[30:31], v[96:97] op_sel_hi:[1,0]
	v_pk_mul_f32 v[28:29], v[28:29], v[96:97] op_sel_hi:[1,0]
	v_pk_mul_f32 v[26:27], v[26:27], v[96:97] op_sel_hi:[1,0]
	v_pk_mul_f32 v[24:25], v[24:25], v[96:97] op_sel_hi:[1,0]
	v_pk_mul_f32 v[22:23], v[22:23], v[96:97] op_sel_hi:[1,0]
	v_pk_mul_f32 v[20:21], v[20:21], v[96:97] op_sel_hi:[1,0]
	v_pk_mul_f32 v[18:19], v[18:19], v[96:97] op_sel_hi:[1,0]
	v_pk_mul_f32 v[16:17], v[16:17], v[96:97] op_sel_hi:[1,0]
	v_pk_mul_f32 v[14:15], v[14:15], v[96:97] op_sel_hi:[1,0]
	v_pk_mul_f32 v[12:13], v[12:13], v[96:97] op_sel_hi:[1,0]
	v_pk_mul_f32 v[10:11], v[10:11], v[96:97] op_sel_hi:[1,0]
	v_pk_mul_f32 v[8:9], v[8:9], v[96:97] op_sel_hi:[1,0]
	v_pk_mul_f32 v[6:7], v[6:7], v[96:97] op_sel_hi:[1,0]
	v_pk_mul_f32 v[4:5], v[4:5], v[96:97] op_sel_hi:[1,0]
	v_pk_mul_f32 v[2:3], v[2:3], v[96:97] op_sel_hi:[1,0]
	v_pk_mul_f32 v[0:1], v[0:1], v[96:97] op_sel_hi:[1,0]

; #define MFMA32(a, b, c) __builtin_amdgcn_mfma_f32_32x32x16_bf16((a), (b), (c), 0, 0, 0)
; #define A_LOAD(tile) do { _Pragma("unroll") for (int i = 0; i < NKC; ++i) kreg[i] = *(const u32x4*)(Kg + (size_t)(tile) * 64 * DQK + i * 32); \
;     _Pragma("unroll") for (int i = 0; i < 4; ++i) vreg[i] = *(const u32x4*)(Vg + (size_t)(tile) * 8192 + i * 2048); } while (0)
; #define A_STORE() do { _Pragma("unroll") for (int i = 0; i < NKC; ++i) *(u32x4*)(Kst + i * 64) = kreg[i]; \
;     _Pragma("unroll") for (int i = 0; i < 4; ++i) *(u32x4*)(Vst + i * 32 * 144) = vreg[i]; } while (0)
;     ...
;     __syncthreads();
;     A_STORE();
;     __syncthreads();
;     if (t + 1 < ntiles) A_LOAD(t0 + t + 1);
;     f32x16 st0, st1;
; #pragma unroll
;     for (int q = 0; q < 16; ++q) { st0[q] = 0.f; st1[q] = 0.f; }
; #pragma unroll
;     for (int ks0 = 0; ks0 < KS; ks0 += 2) {
;       bf16x8 a0[2], a1[2];
; #pragma unroll
;       for (int j = 0; j < 2; ++j) { a0[j] = *(const bf16x8*)(Krd + (ks0 + j) * 32); a1[j] = *(const bf16x8*)(Krd + 32 * KROW + (ks0 + j) * 32); }
;       __builtin_amdgcn_sched_barrier(0);
; #pragma unroll
;       for (int j = 0; j < 2; ++j) { st0 = MFMA32(a0[j], qr[ks0 + j], st0); st1 = MFMA32(a1[j], qr[ks0 + j], st1); }
;     }
;     float mx = st0[0];
; #pragma unroll
;     for (int q = 1; q < 16; ++q) mx = fmaxf(mx, st0[q]);
; #pragma unroll
;     for (int q = 0; q < 16; ++q) mx = fmaxf(mx, st1[q]);
;     mx = fmaxf(mx, __shfl_xor(mx, 32));
;     const float mnew = fmaxf(m, mx * scale_log2);
;     const float alpha = __builtin_amdgcn_exp2f(m - mnew);
;     m = mnew;
;     float ps = 0.f;
; #pragma unroll
;     for (int q = 0; q < 16; ++q) { st0[q] = __builtin_amdgcn_exp2f(st0[q] * scale_log2 - mnew); ps += st0[q]; }
; #pragma unroll
;     for (int q = 0; q < 16; ++q) { st1[q] = __builtin_amdgcn_exp2f(st1[q] * scale_log2 - mnew); ps += st1[q]; }
;     lsum = lsum * alpha + ps;
;     if (!__all(alpha == 1.f)) {
.LBB0_150:
	s_waitcnt vmcnt(29) lgkmcnt(0)
	v_lshl_add_u64 v[64:65], s[94:95], 0, v[192:193]
	s_barrier
	s_waitcnt vmcnt(9)
	ds_write_b128 v199, v[146:149]
	s_waitcnt vmcnt(8)
	ds_write_b128 v199, v[150:153] offset:64
	s_waitcnt vmcnt(7)
	ds_write_b128 v199, v[154:157] offset:128
	s_waitcnt vmcnt(6)
	ds_write_b128 v199, v[158:161] offset:192
	s_waitcnt vmcnt(5)
	ds_write_b128 v199, v[162:165] offset:256
	s_waitcnt vmcnt(4)
	ds_write_b128 v199, v[166:169] offset:320
	s_waitcnt vmcnt(1)
	ds_write_b128 v198, v[178:181] offset:25600
	ds_write_b128 v198, v[170:173] offset:30208
	ds_write_b128 v198, v[174:177] offset:34816
	s_waitcnt vmcnt(0)
	ds_write_b128 v198, v[182:185] offset:39424
	s_waitcnt lgkmcnt(0)
	s_barrier
	global_load_dwordx4 v[146:149], v[64:65], off offset:-192
	global_load_dwordx4 v[150:153], v[64:65], off offset:-128
	global_load_dwordx4 v[154:157], v[64:65], off offset:-64
	global_load_dwordx4 v[158:161], v[64:65], off
	global_load_dwordx4 v[162:165], v[64:65], off offset:64
	global_load_dwordx4 v[166:169], v[64:65], off offset:128
	v_lshl_add_u64 v[64:65], s[94:95], 0, v[190:191]
	v_add_co_u32_e32 v66, vcc, s70, v64
	s_nop 1
	v_addc_co_u32_e32 v67, vcc, 0, v65, vcc
	v_add_co_u32_e32 v64, vcc, s71, v64
	global_load_dwordx4 v[178:181], v[66:67], off offset:-4096
	global_load_dwordx4 v[170:173], v[66:67], off
	v_addc_co_u32_e32 v65, vcc, 0, v65, vcc
	global_load_dwordx4 v[174:177], v[64:65], off offset:-4096
	global_load_dwordx4 v[182:185], v[64:65], off
	ds_read_b128 v[64:67], v197
	ds_read_b128 v[244:247], v197 offset:32
	ds_read_b128 v[68:71], v197 offset:12800
	ds_read_b128 v[248:251], v197 offset:12832
	s_waitcnt lgkmcnt(3)
	v_mfma_f32_32x32x16_bf16 v[80:95], v[64:67], v[142:145], 0
	s_waitcnt lgkmcnt(1)
	v_mfma_f32_32x32x16_bf16 v[64:79], v[68:71], v[142:145], 0
	v_mfma_f32_32x32x16_bf16 v[80:95], v[244:247], v[138:141], v[80:95]
	s_waitcnt lgkmcnt(0)
	v_mfma_f32_32x32x16_bf16 v[64:79], v[248:251], v[138:141], v[64:79]
	ds_read_b128 v[244:247], v197 offset:12864
	ds_read_b128 v[248:251], v197 offset:64
	ds_read_b128 v[238:241], v197 offset:96
	ds_read_b128 v[218:221], v197 offset:12896
	s_waitcnt lgkmcnt(2)
	v_mfma_f32_32x32x16_bf16 v[80:95], v[248:251], v[134:137], v[80:95]
	v_mfma_f32_32x32x16_bf16 v[64:79], v[244:247], v[134:137], v[64:79]
	s_waitcnt lgkmcnt(1)
	v_mfma_f32_32x32x16_bf16 v[80:95], v[238:241], v[130:133], v[80:95]
	s_waitcnt lgkmcnt(0)
	v_mfma_f32_32x32x16_bf16 v[64:79], v[218:221], v[130:133], v[64:79]
	ds_read_b128 v[218:221], v197 offset:12928
	ds_read_b128 v[238:241], v197 offset:128
	ds_read_b128 v[244:247], v197 offset:160
	ds_read_b128 v[248:251], v197 offset:12960
	s_waitcnt lgkmcnt(2)
	v_mfma_f32_32x32x16_bf16 v[80:95], v[238:241], v[126:129], v[80:95]
	v_mfma_f32_32x32x16_bf16 v[64:79], v[218:221], v[126:129], v[64:79]
	s_waitcnt lgkmcnt(1)
	v_mfma_f32_32x32x16_bf16 v[80:95], v[244:247], v[122:125], v[80:95]
	s_waitcnt lgkmcnt(0)
	v_mfma_f32_32x32x16_bf16 v[64:79], v[248:251], v[122:125], v[64:79]
	ds_read_b128 v[218:221], v197 offset:12992
	ds_read_b128 v[238:241], v197 offset:192
	ds_read_b128 v[244:247], v197 offset:224
	ds_read_b128 v[248:251], v197 offset:13024
	s_waitcnt lgkmcnt(2)
	v_mfma_f32_32x32x16_bf16 v[80:95], v[238:241], v[118:121], v[80:95]
	v_mfma_f32_32x32x16_bf16 v[64:79], v[218:221], v[118:121], v[64:79]
	s_waitcnt lgkmcnt(1)
	v_mfma_f32_32x32x16_bf16 v[80:95], v[244:247], v[114:117], v[80:95]
	s_waitcnt lgkmcnt(0)
	v_mfma_f32_32x32x16_bf16 v[64:79], v[248:251], v[114:117], v[64:79]
	ds_read_b128 v[218:221], v197 offset:13056
	ds_read_b128 v[238:241], v197 offset:256
	ds_read_b128 v[244:247], v197 offset:288
	ds_read_b128 v[248:251], v197 offset:13088
	s_waitcnt lgkmcnt(2)
	v_mfma_f32_32x32x16_bf16 v[80:95], v[238:241], v[110:113], v[80:95]
	v_mfma_f32_32x32x16_bf16 v[64:79], v[218:221], v[110:113], v[64:79]
	s_waitcnt lgkmcnt(1)
	v_mfma_f32_32x32x16_bf16 v[80:95], v[244:247], v[106:109], v[80:95]
	s_waitcnt lgkmcnt(0)
	v_mfma_f32_32x32x16_bf16 v[64:79], v[248:251], v[106:109], v[64:79]
	ds_read_b128 v[218:221], v197 offset:13120
	ds_read_b128 v[238:241], v197 offset:320
	ds_read_b128 v[244:247], v197 offset:352
	ds_read_b128 v[248:251], v197 offset:13152
	s_waitcnt lgkmcnt(2)
	v_mfma_f32_32x32x16_bf16 v[80:95], v[238:241], v[102:105], v[80:95]
	v_mov_b32_e32 v202, v196
	s_waitcnt lgkmcnt(1)
	v_mfma_f32_32x32x16_bf16 v[80:95], v[244:247], v[98:101], v[80:95]
	v_mfma_f32_32x32x16_bf16 v[64:79], v[218:221], v[102:105], v[64:79]
	s_nop 10
	v_max_f32_e32 v96, v81, v81
	v_max_f32_e32 v200, v80, v80
	v_max_f32_e32 v96, v200, v96
	v_max3_f32 v96, v96, v82, v83
	v_max3_f32 v96, v96, v84, v85
	v_max3_f32 v96, v96, v86, v87
	v_max3_f32 v96, v96, v88, v89
	s_waitcnt lgkmcnt(0)
	v_mfma_f32_32x32x16_bf16 v[64:79], v[248:251], v[98:101], v[64:79]
	v_max3_f32 v96, v96, v90, v91
	v_max3_f32 v96, v96, v92, v93
	v_max3_f32 v96, v96, v94, v95
	s_nop 8
	v_max3_f32 v96, v96, v64, v65
	v_max3_f32 v96, v96, v66, v67
	v_max3_f32 v96, v96, v68, v69
	v_max3_f32 v96, v96, v70, v71
	v_max3_f32 v96, v96, v72, v73
	v_max3_f32 v96, v96, v74, v75
	v_max3_f32 v96, v96, v76, v77
	v_max3_f32 v96, v96, v78, v79
	v_mov_b32_e32 v200, v96
	v_mov_b32_e32 v196, v96
	s_nop 1
	v_permlane32_swap_b32_e32 v200, v196
	s_waitcnt lgkmcnt(0)
	v_max_f32_e32 v96, v200, v196
	v_mul_f32_e32 v96, 0x3dd53b94, v96
	v_max_f32_e32 v196, v202, v202
	v_max_f32_e32 v196, v196, v96
	v_sub_f32_e32 v96, v202, v196
	v_exp_f32_e32 v96, v96
	s_nop 0
	v_cmp_eq_f32_e32 vcc, 1.0, v96
	s_cmp_eq_u64 vcc, exec
	s_cbranch_scc1 .LBB0_152
;     ...
;     if (!__all(alpha == 1.f)) {
; #pragma unroll
;       for (int n = 0; n < 4; ++n)
; #pragma unroll
;         for (int q = 0; q < 16; ++q) ot[n][q] *= alpha;
;     }
	v_pk_mul_f32 v[62:63], v[62:63], v[96:97] op_sel_hi:[1,0]
	v_pk_mul_f32 v[60:61], v[60:61], v[96:97] op_sel_hi:[1,0]
	v_pk_mul_f32 v[58:59], v[58:59], v[96:97] op_sel_hi:[1,0]
	v_pk_mul_f32 v[56:57], v[56:57], v[96:97] op_sel_hi:[1,0]
	v_pk_mul_f32 v[54:55], v[54:55], v[96:97] op_sel_hi:[1,0]
	v_pk_mul_f32 v[52:53], v[52:53], v[96:97] op_sel_hi:[1,0]
	v_pk_mul_f32 v[50:51], v[50:51], v[96:97] op_sel_hi:[1,0]
	v_pk_mul_f32 v[48:49], v[48:49], v[96:97] op_sel_hi:[1,0]
	v_pk_mul_f32 v[46:47], v[46:47], v[96:97] op_sel_hi:[1,0]
	v_pk_mul_f32 v[44:45], v[44:45], v[96:97] op_sel_hi:[1,0]
	v_pk_mul_f32 v[42:43], v[42:43], v[96:97] op_sel_hi:[1,0]
	v_pk_mul_f32 v[40:41], v[40:41], v[96:97] op_sel_hi:[1,0]
	v_pk_mul_f32 v[38:39], v[38:39], v[96:97] op_sel_hi:[1,0]
	v_pk_mul_f32 v[36:37], v[36:37], v[96:97] op_sel_hi:[1,0]
	v_pk_mul_f32 v[34:35], v[34:35], v[96:97] op_sel_hi:[1,0]
	v_pk_mul_f32 v[32:33], v[32:33], v[96:97] op_sel_hi:[1,0]
	v_pk_mul_f32 v[30:31], v[30:31], v[96:97] op_sel_hi:[1,0]
	v_pk_mul_f32 v[28:29], v[28:29], v[96:97] op_sel_hi:[1,0]
	v_pk_mul_f32 v[26:27], v[26:27], v[96:97] op_sel_hi:[1,0]
	v_pk_mul_f32 v[24:25], v[24:25], v[96:97] op_sel_hi:[1,0]
	v_pk_mul_f32 v[22:23], v[22:23], v[96:97] op_sel_hi:[1,0]
	v_pk_mul_f32 v[20:21], v[20:21], v[96:97] op_sel_hi:[1,0]
	v_pk_mul_f32 v[18:19], v[18:19], v[96:97] op_sel_hi:[1,0]
	v_pk_mul_f32 v[16:17], v[16:17], v[96:97] op_sel_hi:[1,0]
	v_pk_mul_f32 v[14:15], v[14:15], v[96:97] op_sel_hi:[1,0]
	v_pk_mul_f32 v[12:13], v[12:13], v[96:97] op_sel_hi:[1,0]
	v_pk_mul_f32 v[10:11], v[10:11], v[96:97] op_sel_hi:[1,0]
	v_pk_mul_f32 v[8:9], v[8:9], v[96:97] op_sel_hi:[1,0]
	v_pk_mul_f32 v[6:7], v[6:7], v[96:97] op_sel_hi:[1,0]
	v_pk_mul_f32 v[4:5], v[4:5], v[96:97] op_sel_hi:[1,0]
	v_pk_mul_f32 v[2:3], v[2:3], v[96:97] op_sel_hi:[1,0]
	v_pk_mul_f32 v[0:1], v[0:1], v[96:97] op_sel_hi:[1,0]
